# FF1 epilogue: ReLU applied to the raw accumulators in the shadow of the row-scale load wait (relu(acc*rs) == relu(acc)*rs, rs > 0), instead of after it
# baseline (speedup 1.0000x reference)
;     __device__ __forceinline__ void operator()(const f32x4 (&acc)[2][2][4][2], const pg8::Unit& u, int wr, int wc, int fr, int fq) const {
;         f32x4 sq[2][4];
; #pragma unroll
;         for (int ai = 0; ai < 2; ++ai)
; #pragma unroll
;             for (int m = 0; m < 4; ++m) sq[ai][m] = *(const f32x4*)(ssqp + (size_t)(u.pm * 256 + ai * 128 + wr * 64 + m * 16 + fr) * 4);
;         __builtin_amdgcn_sched_barrier(0);
;     ...
;                         for (int e = 0; e < 4; ++e) { const float h = fmaxf(acc[ai][bj][m][n][e] * rn, 0.f); y[n * 4 + e] = h * h; }
.Lh_ok:
	v_lshl_add_u32 v166, s30, 8, v174
	v_or_b32_e32 v198, 16, v166
	v_ashrrev_i32_e32 v167, 31, v166
	v_ashrrev_i32_e32 v199, 31, v198
	v_or_b32_e32 v200, 32, v166
	v_or_b32_e32 v172, 48, v166
	v_lshl_add_u64 v[128:129], v[166:167], 4, s[8:9]
	v_lshl_add_u64 v[130:131], v[198:199], 4, s[8:9]
	v_ashrrev_i32_e32 v201, 31, v200
	v_ashrrev_i32_e32 v173, 31, v172
	v_add_u32_e32 v170, 0x80, v166
	v_add_u32_e32 v168, 0x90, v166
	global_load_dwordx4 v[180:183], v[128:129], off
	global_load_dwordx4 v[186:189], v[130:131], off
	v_lshl_add_u64 v[128:129], v[200:201], 4, s[8:9]
	v_lshl_add_u64 v[130:131], v[172:173], 4, s[8:9]
	v_ashrrev_i32_e32 v171, 31, v170
	v_ashrrev_i32_e32 v169, 31, v168
	v_add_u32_e32 v164, 0xa0, v166
	v_add_u32_e32 v162, 0xb0, v166
	global_load_dwordx4 v[190:193], v[128:129], off
	global_load_dwordx4 v[194:197], v[130:131], off
	v_lshl_add_u64 v[128:129], v[170:171], 4, s[8:9]
	v_lshl_add_u64 v[130:131], v[168:169], 4, s[8:9]
	v_ashrrev_i32_e32 v165, 31, v164
	v_ashrrev_i32_e32 v163, 31, v162
	global_load_dwordx4 v[140:143], v[128:129], off
	global_load_dwordx4 v[136:139], v[130:131], off
	v_lshl_add_u64 v[128:129], v[164:165], 4, s[8:9]
	v_lshl_add_u64 v[130:131], v[162:163], 4, s[8:9]
	global_load_dwordx4 v[132:135], v[128:129], off
	s_nop 0
	global_load_dwordx4 v[128:131], v[130:131], off
	v_lshlrev_b64 v[166:167], 13, v[166:167]
	v_max_f32_e32 v0, 0, v0
	v_max_f32_e32 v1, 0, v1
	v_max_f32_e32 v2, 0, v2
	v_max_f32_e32 v3, 0, v3
	v_max_f32_e32 v4, 0, v4
	v_max_f32_e32 v5, 0, v5
	v_max_f32_e32 v6, 0, v6
	v_max_f32_e32 v7, 0, v7
	v_max_f32_e32 v8, 0, v8
	v_max_f32_e32 v9, 0, v9
	v_max_f32_e32 v10, 0, v10
	v_max_f32_e32 v11, 0, v11
	v_max_f32_e32 v12, 0, v12
	v_max_f32_e32 v13, 0, v13
	v_max_f32_e32 v14, 0, v14
	v_max_f32_e32 v15, 0, v15
	v_max_f32_e32 v16, 0, v16
	v_max_f32_e32 v17, 0, v17
	v_max_f32_e32 v18, 0, v18
	v_max_f32_e32 v19, 0, v19
	v_max_f32_e32 v20, 0, v20
	v_max_f32_e32 v21, 0, v21
	v_max_f32_e32 v22, 0, v22
	v_max_f32_e32 v23, 0, v23
	v_max_f32_e32 v24, 0, v24
	v_max_f32_e32 v25, 0, v25
	v_max_f32_e32 v26, 0, v26
	v_max_f32_e32 v27, 0, v27
	v_max_f32_e32 v28, 0, v28
	v_max_f32_e32 v29, 0, v29
	v_max_f32_e32 v30, 0, v30
	v_max_f32_e32 v31, 0, v31
	v_max_f32_e32 v32, 0, v32
	v_max_f32_e32 v33, 0, v33
	v_max_f32_e32 v34, 0, v34
	v_max_f32_e32 v35, 0, v35
	v_max_f32_e32 v36, 0, v36
	v_max_f32_e32 v37, 0, v37
	v_max_f32_e32 v38, 0, v38
	v_max_f32_e32 v39, 0, v39
	v_max_f32_e32 v40, 0, v40
	v_max_f32_e32 v41, 0, v41
	v_max_f32_e32 v42, 0, v42
	v_max_f32_e32 v43, 0, v43
	v_max_f32_e32 v44, 0, v44
	v_max_f32_e32 v45, 0, v45
	v_max_f32_e32 v46, 0, v46
	v_max_f32_e32 v47, 0, v47
	v_max_f32_e32 v48, 0, v48
	v_max_f32_e32 v49, 0, v49
	v_max_f32_e32 v50, 0, v50
	v_max_f32_e32 v51, 0, v51
	v_max_f32_e32 v52, 0, v52
	v_max_f32_e32 v53, 0, v53
	v_max_f32_e32 v54, 0, v54
	v_max_f32_e32 v55, 0, v55
	v_max_f32_e32 v56, 0, v56
	v_max_f32_e32 v57, 0, v57
	v_max_f32_e32 v58, 0, v58
	v_max_f32_e32 v59, 0, v59
	v_max_f32_e32 v60, 0, v60
	v_max_f32_e32 v61, 0, v61
	v_max_f32_e32 v62, 0, v62
	v_max_f32_e32 v63, 0, v63
	v_max_f32_e32 v64, 0, v64
	v_max_f32_e32 v65, 0, v65
	v_max_f32_e32 v66, 0, v66
	v_max_f32_e32 v67, 0, v67
	v_max_f32_e32 v68, 0, v68
	v_max_f32_e32 v69, 0, v69
	v_max_f32_e32 v70, 0, v70
	v_max_f32_e32 v71, 0, v71
	v_max_f32_e32 v72, 0, v72
	v_max_f32_e32 v73, 0, v73
	v_max_f32_e32 v74, 0, v74
	v_max_f32_e32 v75, 0, v75
	v_max_f32_e32 v76, 0, v76
	v_max_f32_e32 v77, 0, v77
	v_max_f32_e32 v78, 0, v78
	v_max_f32_e32 v79, 0, v79
	v_max_f32_e32 v80, 0, v80
	v_max_f32_e32 v81, 0, v81
	v_max_f32_e32 v82, 0, v82
	v_max_f32_e32 v83, 0, v83
	v_max_f32_e32 v84, 0, v84
	v_max_f32_e32 v85, 0, v85
	v_max_f32_e32 v86, 0, v86
	v_max_f32_e32 v87, 0, v87
	v_max_f32_e32 v88, 0, v88
	v_max_f32_e32 v89, 0, v89
	v_max_f32_e32 v90, 0, v90
	v_max_f32_e32 v91, 0, v91
	v_max_f32_e32 v92, 0, v92
	v_max_f32_e32 v93, 0, v93
	v_max_f32_e32 v94, 0, v94
	v_max_f32_e32 v95, 0, v95
	v_max_f32_e32 v96, 0, v96
	v_max_f32_e32 v97, 0, v97
	v_max_f32_e32 v98, 0, v98
	v_max_f32_e32 v99, 0, v99
	v_max_f32_e32 v100, 0, v100
	v_max_f32_e32 v101, 0, v101
	v_max_f32_e32 v102, 0, v102
	v_max_f32_e32 v103, 0, v103
	v_max_f32_e32 v104, 0, v104
	v_max_f32_e32 v105, 0, v105
	v_max_f32_e32 v106, 0, v106
	v_max_f32_e32 v107, 0, v107
	v_max_f32_e32 v108, 0, v108
	v_max_f32_e32 v109, 0, v109
	v_max_f32_e32 v110, 0, v110
	v_max_f32_e32 v111, 0, v111
	v_max_f32_e32 v112, 0, v112
	v_max_f32_e32 v113, 0, v113
	v_max_f32_e32 v114, 0, v114
	v_max_f32_e32 v115, 0, v115
	v_max_f32_e32 v116, 0, v116
	v_max_f32_e32 v117, 0, v117
	v_max_f32_e32 v118, 0, v118
	v_max_f32_e32 v119, 0, v119
	v_max_f32_e32 v120, 0, v120
	v_max_f32_e32 v121, 0, v121
	v_max_f32_e32 v122, 0, v122
	v_max_f32_e32 v123, 0, v123
	v_max_f32_e32 v124, 0, v124
	v_max_f32_e32 v125, 0, v125
	v_max_f32_e32 v126, 0, v126
	v_max_f32_e32 v127, 0, v127
	s_waitcnt vmcnt(0)
;     __device__ __forceinline__ void operator()(const f32x4 (&acc)[2][2][4][2], const pg8::Unit& u, int wr, int wc, int fr, int fq) const {
;     ...
;         for (int ai = 0; ai < 2; ++ai)
; #pragma unroll
;             for (int m = 0; m < 4; ++m) {
;                 const int row = u.pm * 256 + ai * 128 + wr * 64 + m * 16 + fr;
;                 const float tot = (sq[ai][m].x + sq[ai][m].y) + (sq[ai][m].z + sq[ai][m].w);
;                 const float rn = rsqrtf(tot * (1.f / 1024.f) + EPS);
; #pragma unroll
;                 for (int bj = 0; bj < 2; ++bj) {
;                     float y[8];
; #pragma unroll
;                     for (int n = 0; n < 2; ++n)
; #pragma unroll
;                         for (int e = 0; e < 4; ++e) { const float h = fmaxf(acc[ai][bj][m][n][e] * rn, 0.f); y[n * 4 + e] = h * h; }
;                     store8(H + (size_t)row * FF + u.pn * 256 + 128 * bj + 32 * wc + 8 * fq, y);
;                 }
	v_mov_b32_e32 v202, v181
	v_mov_b32_e32 v203, v182
	v_mov_b32_e32 v181, v183
	v_lshl_add_u64 v[182:183], s[10:11], 0, v[166:167]
	v_mov_b32_e32 v166, v187
	v_mov_b32_e32 v167, v188
	v_mov_b32_e32 v187, v189
	v_pk_add_f32 v[180:181], v[202:203], v[180:181]
	v_pk_add_f32 v[166:167], v[166:167], v[186:187]
	v_mov_b32_e32 v187, v180
	v_mov_b32_e32 v186, v166
	v_mov_b32_e32 v180, v167
	v_pk_add_f32 v[180:181], v[186:187], v[180:181]
	v_mov_b64_e32 v[166:167], s[20:21]
	v_pk_fma_f32 v[180:181], v[180:181], s[18:19], v[166:167] op_sel_hi:[1,0,0]
	s_lshl_b32 s30, s31, 8
	v_mul_f32_e32 v179, 0x4b800000, v181
	v_cmp_gt_f32_e32 vcc, s50, v181
	s_ashr_i32 s31, s30, 31
	s_lshl_b64 s[30:31], s[30:31], 1
	v_cndmask_b32_e32 v179, v181, v179, vcc
	v_rsq_f32_e32 v179, v179
	v_lshl_add_u64 v[182:183], v[182:183], 0, s[30:31]
	v_lshl_add_u64 v[182:183], v[182:183], 0, s[4:5]
	v_lshl_add_u64 v[182:183], v[182:183], 0, v[152:153]
	v_mul_f32_e32 v181, 0x45800000, v179
	v_cndmask_b32_e32 v179, v179, v181, vcc
	v_mul_f32_e32 v120, v120, v179
	v_mul_f32_e32 v181, v120, v120
	v_mul_f32_e32 v120, v121, v179
	v_mul_f32_e32 v185, v120, v120
	v_mul_f32_e32 v120, v122, v179
	v_mul_f32_e32 v124, v124, v179
	v_mul_f32_e32 v125, v125, v179
	v_mul_f32_e32 v186, v120, v120
	v_mul_f32_e32 v120, v123, v179
	v_mul_f32_e32 v126, v126, v179
	v_mul_f32_e32 v127, v127, v179
	v_mul_f32_e32 v112, v112, v179
	v_mul_f32_e32 v124, v124, v124
	v_mul_f32_e32 v125, v125, v125
	v_mul_f32_e32 v123, v120, v120
	v_cvt_pk_bf16_f32 v120, v124, v125
	v_mul_f32_e32 v126, v126, v126
	v_mul_f32_e32 v127, v127, v127
	v_cvt_pk_bf16_f32 v121, v126, v127
	v_cvt_pk_bf16_f32 v122, v181, v185
	v_cvt_pk_bf16_f32 v123, v186, v123
	global_store_dwordx4 v[182:183], v[120:123], off nt
	v_mul_f32_e32 v116, v116, v179
	s_nop 0
	v_mul_f32_e32 v120, v112, v112
	v_mul_f32_e32 v112, v113, v179
	v_mul_f32_e32 v121, v112, v112
	v_mul_f32_e32 v112, v114, v179
	v_mul_f32_e32 v117, v117, v179
	v_mul_f32_e32 v122, v112, v112
	v_mul_f32_e32 v112, v115, v179
	v_mul_f32_e32 v114, 0x4b800000, v180
	v_cmp_gt_f32_e32 vcc, s50, v180
	v_mul_f32_e32 v116, v116, v116
	s_nop 0
	v_cndmask_b32_e32 v114, v180, v114, vcc
	v_mul_f32_e32 v117, v117, v117
	v_mul_f32_e32 v115, v112, v112
	v_cvt_pk_bf16_f32 v112, v116, v117
	v_rsq_f32_e32 v116, v114
	v_mul_f32_e32 v118, v118, v179
	v_mul_f32_e32 v119, v119, v179
	v_mul_f32_e32 v118, v118, v118
	v_mul_f32_e32 v119, v119, v119
	v_cvt_pk_bf16_f32 v113, v118, v119
	v_cvt_pk_bf16_f32 v114, v120, v121
	v_cvt_pk_bf16_f32 v115, v122, v115
	global_store_dwordx4 v[182:183], v[112:115], off offset:256 nt
	s_nop 1
	v_mul_f32_e32 v112, 0x45800000, v116
	v_cndmask_b32_e32 v114, v116, v112, vcc
	v_mul_f32_e32 v104, v104, v114
	v_mul_f32_e32 v117, v104, v104
	v_mul_f32_e32 v104, v105, v114
	v_mul_f32_e32 v108, v108, v114
	v_mul_f32_e32 v118, v104, v104
	v_mul_f32_e32 v104, v106, v114
	v_mul_f32_e32 v115, v108, v108
	v_mul_f32_e32 v108, v109, v114
	v_mul_f32_e32 v119, v104, v104
	v_mul_f32_e32 v104, v107, v114
	v_lshlrev_b64 v[112:113], 13, v[198:199]
	v_mul_f32_e32 v116, v108, v108
	v_mul_f32_e32 v108, v110, v114
	v_mul_f32_e32 v107, v104, v104
	v_lshl_add_u64 v[104:105], s[10:11], 0, v[112:113]
	v_mul_f32_e32 v110, v108, v108
	v_mul_f32_e32 v108, v111, v114
	v_lshl_add_u64 v[104:105], v[104:105], 0, s[30:31]
	v_lshl_add_u64 v[104:105], v[104:105], 0, s[4:5]
	v_mul_f32_e32 v96, v96, v114
	v_mul_f32_e32 v111, v108, v108
	v_lshl_add_u64 v[108:109], v[104:105], 0, v[152:153]
	v_cvt_pk_bf16_f32 v104, v115, v116
	v_cvt_pk_bf16_f32 v105, v110, v111
	v_cvt_pk_bf16_f32 v106, v117, v118
	v_cvt_pk_bf16_f32 v107, v119, v107
	global_store_dwordx4 v[108:109], v[104:107], off nt
	v_mul_f32_e32 v100, v100, v114
	v_mul_f32_e32 v101, v101, v114
	v_mul_f32_e32 v104, v96, v96
	v_mul_f32_e32 v96, v97, v114
	v_mul_f32_e32 v105, v96, v96
	v_mul_f32_e32 v96, v98, v114
	v_mul_f32_e32 v102, v102, v114
	v_mul_f32_e32 v103, v103, v114
	v_mul_f32_e32 v106, v96, v96
	v_mul_f32_e32 v96, v99, v114
	v_mul_f32_e32 v100, v100, v100
	v_mul_f32_e32 v101, v101, v101
	v_mul_f32_e32 v102, v102, v102
	v_mul_f32_e32 v103, v103, v103
	v_mul_f32_e32 v99, v96, v96
	v_cvt_pk_bf16_f32 v96, v100, v101
	v_cvt_pk_bf16_f32 v97, v102, v103
	v_cvt_pk_bf16_f32 v98, v104, v105
	v_cvt_pk_bf16_f32 v99, v106, v99
	global_store_dwordx4 v[108:109], v[96:99], off offset:256 nt
	v_mov_b32_e32 v100, v195
	v_mov_b32_e32 v101, v196
	v_mov_b32_e32 v96, v191
	v_mov_b32_e32 v97, v192
	v_mov_b32_e32 v191, v193
	v_mov_b32_e32 v195, v197
	v_pk_add_f32 v[96:97], v[96:97], v[190:191]
	v_pk_add_f32 v[100:101], v[100:101], v[194:195]
	v_mov_b32_e32 v103, v96
	v_mov_b32_e32 v102, v100
	v_mov_b32_e32 v96, v101
	v_pk_add_f32 v[96:97], v[102:103], v[96:97]
	v_lshlrev_b64 v[98:99], 13, v[200:201]
	v_pk_fma_f32 v[96:97], v[96:97], s[18:19], v[166:167] op_sel_hi:[1,0,0]
	v_lshl_add_u64 v[98:99], s[10:11], 0, v[98:99]
	v_mul_f32_e32 v100, 0x4b800000, v97
	v_cmp_gt_f32_e32 vcc, s50, v97
	v_lshl_add_u64 v[98:99], v[98:99], 0, s[30:31]
	v_lshl_add_u64 v[98:99], v[98:99], 0, s[4:5]
	v_cndmask_b32_e32 v97, v97, v100, vcc
	v_rsq_f32_e32 v97, v97
	v_lshl_add_u64 v[98:99], v[98:99], 0, v[152:153]
	v_mul_f32_e32 v100, 0x45800000, v97
	v_cndmask_b32_e32 v97, v97, v100, vcc
	v_mul_f32_e32 v88, v88, v97
	v_mul_f32_e32 v100, v88, v88
	v_mul_f32_e32 v88, v89, v97
	v_mul_f32_e32 v101, v88, v88
	v_mul_f32_e32 v88, v90, v97
	v_mul_f32_e32 v92, v92, v97
	v_mul_f32_e32 v93, v93, v97
	v_mul_f32_e32 v102, v88, v88
	v_mul_f32_e32 v88, v91, v97
	v_mul_f32_e32 v94, v94, v97
	v_mul_f32_e32 v95, v95, v97
	v_mul_f32_e32 v80, v80, v97
	v_mul_f32_e32 v92, v92, v92
	v_mul_f32_e32 v93, v93, v93
	v_mul_f32_e32 v91, v88, v88
;     __device__ __forceinline__ void operator()(const f32x4 (&acc)[2][2][4][2], const pg8::Unit& u, int wr, int wc, int fr, int fq) const {
;     ...
;         for (int ai = 0; ai < 2; ++ai)
; #pragma unroll
;             for (int m = 0; m < 4; ++m) {
;                 const int row = u.pm * 256 + ai * 128 + wr * 64 + m * 16 + fr;
;                 const float tot = (sq[ai][m].x + sq[ai][m].y) + (sq[ai][m].z + sq[ai][m].w);
;                 const float rn = rsqrtf(tot * (1.f / 1024.f) + EPS);
; #pragma unroll
;                 for (int bj = 0; bj < 2; ++bj) {
;                     float y[8];
; #pragma unroll
;                     for (int n = 0; n < 2; ++n)
; #pragma unroll
;                         for (int e = 0; e < 4; ++e) { const float h = fmaxf(acc[ai][bj][m][n][e] * rn, 0.f); y[n * 4 + e] = h * h; }
;                     store8(H + (size_t)row * FF + u.pn * 256 + 128 * bj + 32 * wc + 8 * fq, y);
;                 }
	v_cvt_pk_bf16_f32 v88, v92, v93
	v_mul_f32_e32 v94, v94, v94
	v_mul_f32_e32 v95, v95, v95
	v_cvt_pk_bf16_f32 v89, v94, v95
	v_cvt_pk_bf16_f32 v90, v100, v101
	v_cvt_pk_bf16_f32 v91, v102, v91
	global_store_dwordx4 v[98:99], v[88:91], off nt
	v_mul_f32_e32 v84, v84, v97
	s_nop 0
	v_mul_f32_e32 v88, v80, v80
	v_mul_f32_e32 v80, v81, v97
	v_mul_f32_e32 v89, v80, v80
	v_mul_f32_e32 v80, v82, v97
	v_mul_f32_e32 v85, v85, v97
	v_mul_f32_e32 v90, v80, v80
	v_mul_f32_e32 v80, v83, v97
	v_mul_f32_e32 v82, 0x4b800000, v96
	v_cmp_gt_f32_e32 vcc, s50, v96
	v_mul_f32_e32 v84, v84, v84
	s_nop 0
	v_cndmask_b32_e32 v82, v96, v82, vcc
	v_mul_f32_e32 v85, v85, v85
	v_mul_f32_e32 v83, v80, v80
	v_cvt_pk_bf16_f32 v80, v84, v85
	v_rsq_f32_e32 v84, v82
	v_mul_f32_e32 v86, v86, v97
	v_mul_f32_e32 v87, v87, v97
	v_mul_f32_e32 v86, v86, v86
	v_mul_f32_e32 v87, v87, v87
	v_cvt_pk_bf16_f32 v81, v86, v87
	v_cvt_pk_bf16_f32 v82, v88, v89
	v_cvt_pk_bf16_f32 v83, v90, v83
	global_store_dwordx4 v[98:99], v[80:83], off offset:256 nt
	s_nop 1
	v_mul_f32_e32 v80, 0x45800000, v84
	v_cndmask_b32_e32 v82, v84, v80, vcc
	v_mul_f32_e32 v72, v72, v82
	v_mul_f32_e32 v85, v72, v72
	v_mul_f32_e32 v72, v73, v82
	v_mul_f32_e32 v76, v76, v82
	v_mul_f32_e32 v86, v72, v72
	v_mul_f32_e32 v72, v74, v82
	v_mul_f32_e32 v83, v76, v76
	v_mul_f32_e32 v76, v77, v82
	v_mul_f32_e32 v87, v72, v72
	v_mul_f32_e32 v72, v75, v82
	v_lshlrev_b64 v[80:81], 13, v[172:173]
	v_mul_f32_e32 v84, v76, v76
	v_mul_f32_e32 v76, v78, v82
	v_mul_f32_e32 v75, v72, v72
	v_lshl_add_u64 v[72:73], s[10:11], 0, v[80:81]
	v_mul_f32_e32 v78, v76, v76
	v_mul_f32_e32 v76, v79, v82
	v_lshl_add_u64 v[72:73], v[72:73], 0, s[30:31]
	v_lshl_add_u64 v[72:73], v[72:73], 0, s[4:5]
	v_mul_f32_e32 v64, v64, v82
	v_mul_f32_e32 v79, v76, v76
	v_lshl_add_u64 v[76:77], v[72:73], 0, v[152:153]
	v_cvt_pk_bf16_f32 v72, v83, v84
	v_cvt_pk_bf16_f32 v73, v78, v79
	v_cvt_pk_bf16_f32 v74, v85, v86
	v_cvt_pk_bf16_f32 v75, v87, v75
	global_store_dwordx4 v[76:77], v[72:75], off nt
	v_mul_f32_e32 v68, v68, v82
	v_mul_f32_e32 v69, v69, v82
	v_mul_f32_e32 v72, v64, v64
	v_mul_f32_e32 v64, v65, v82
	v_mul_f32_e32 v73, v64, v64
	v_mul_f32_e32 v64, v66, v82
	v_mul_f32_e32 v70, v70, v82
	v_mul_f32_e32 v71, v71, v82
	v_mul_f32_e32 v74, v64, v64
	v_mul_f32_e32 v64, v67, v82
	v_mul_f32_e32 v68, v68, v68
	v_mul_f32_e32 v69, v69, v69
	v_mul_f32_e32 v70, v70, v70
	v_mul_f32_e32 v71, v71, v71
	v_mul_f32_e32 v67, v64, v64
	v_cvt_pk_bf16_f32 v64, v68, v69
	v_cvt_pk_bf16_f32 v65, v70, v71
	v_cvt_pk_bf16_f32 v66, v72, v73
	v_cvt_pk_bf16_f32 v67, v74, v67
	global_store_dwordx4 v[76:77], v[64:67], off offset:256 nt
	v_mov_b32_e32 v68, v137
	v_mov_b32_e32 v69, v138
	v_mov_b32_e32 v64, v141
	v_mov_b32_e32 v65, v142
	v_mov_b32_e32 v141, v143
	v_mov_b32_e32 v137, v139
	v_pk_add_f32 v[64:65], v[64:65], v[140:141]
	v_pk_add_f32 v[68:69], v[68:69], v[136:137]
	v_mov_b32_e32 v71, v64
	v_mov_b32_e32 v70, v68
	v_mov_b32_e32 v64, v69
	v_pk_add_f32 v[64:65], v[70:71], v[64:65]
	v_lshlrev_b64 v[66:67], 13, v[170:171]
	v_pk_fma_f32 v[64:65], v[64:65], s[18:19], v[166:167] op_sel_hi:[1,0,0]
	v_lshl_add_u64 v[66:67], s[10:11], 0, v[66:67]
	v_mul_f32_e32 v68, 0x4b800000, v65
	v_cmp_gt_f32_e32 vcc, s50, v65
	v_lshl_add_u64 v[66:67], v[66:67], 0, s[30:31]
	v_lshl_add_u64 v[66:67], v[66:67], 0, s[4:5]
	v_cndmask_b32_e32 v65, v65, v68, vcc
	v_rsq_f32_e32 v65, v65
	v_lshl_add_u64 v[66:67], v[66:67], 0, v[152:153]
	v_mul_f32_e32 v68, 0x45800000, v65
	v_cndmask_b32_e32 v65, v65, v68, vcc
	v_mul_f32_e32 v56, v56, v65
	v_mul_f32_e32 v68, v56, v56
	v_mul_f32_e32 v56, v57, v65
	v_mul_f32_e32 v69, v56, v56
	v_mul_f32_e32 v56, v58, v65
	v_mul_f32_e32 v60, v60, v65
	v_mul_f32_e32 v61, v61, v65
	v_mul_f32_e32 v70, v56, v56
	v_mul_f32_e32 v56, v59, v65
	v_mul_f32_e32 v62, v62, v65
	v_mul_f32_e32 v63, v63, v65
	v_mul_f32_e32 v48, v48, v65
	v_mul_f32_e32 v60, v60, v60
	v_mul_f32_e32 v61, v61, v61
	v_mul_f32_e32 v59, v56, v56
	v_cvt_pk_bf16_f32 v56, v60, v61
	v_mul_f32_e32 v62, v62, v62
	v_mul_f32_e32 v63, v63, v63
	v_cvt_pk_bf16_f32 v57, v62, v63
	v_cvt_pk_bf16_f32 v58, v68, v69
	v_cvt_pk_bf16_f32 v59, v70, v59
	global_store_dwordx4 v[66:67], v[56:59], off nt
	v_mul_f32_e32 v52, v52, v65
	s_nop 0
	v_mul_f32_e32 v56, v48, v48
	v_mul_f32_e32 v48, v49, v65
	v_mul_f32_e32 v57, v48, v48
	v_mul_f32_e32 v48, v50, v65
	v_mul_f32_e32 v53, v53, v65
	v_mul_f32_e32 v58, v48, v48
	v_mul_f32_e32 v48, v51, v65
	v_mul_f32_e32 v50, 0x4b800000, v64
	v_cmp_gt_f32_e32 vcc, s50, v64
	v_mul_f32_e32 v52, v52, v52
	s_nop 0
	v_cndmask_b32_e32 v50, v64, v50, vcc
	v_mul_f32_e32 v53, v53, v53
	v_mul_f32_e32 v51, v48, v48
	v_cvt_pk_bf16_f32 v48, v52, v53
	v_rsq_f32_e32 v52, v50
	v_mul_f32_e32 v54, v54, v65
	v_mul_f32_e32 v55, v55, v65
	v_mul_f32_e32 v54, v54, v54
	v_mul_f32_e32 v55, v55, v55
	v_cvt_pk_bf16_f32 v49, v54, v55
	v_cvt_pk_bf16_f32 v50, v56, v57
	v_cvt_pk_bf16_f32 v51, v58, v51
	global_store_dwordx4 v[66:67], v[48:51], off offset:256 nt
	s_nop 1
	v_mul_f32_e32 v48, 0x45800000, v52
	v_cndmask_b32_e32 v50, v52, v48, vcc
	v_mul_f32_e32 v40, v40, v50
	v_mul_f32_e32 v53, v40, v40
	v_mul_f32_e32 v40, v41, v50
	v_mul_f32_e32 v44, v44, v50
	v_mul_f32_e32 v54, v40, v40
	v_mul_f32_e32 v40, v42, v50
	v_mul_f32_e32 v51, v44, v44
	v_mul_f32_e32 v44, v45, v50
	v_mul_f32_e32 v55, v40, v40
; #define PG8_BAR __builtin_amdgcn_s_barrier()
; template <class Epi, class Sched, bool ALIGN_EPI = false, bool SP2 = false>
; __device__ __forceinline__ void gemm_phase(PG8_LAS unsigned char* lds, const Gemm g, const Sched& S, const Epi& E) {
;     ...
;         if constexpr (ALIGN_EPI) { if (wr == 0) PG8_BAR; }
;         if constexpr (!Epi::AFTER_DRAIN) { E(acc, cur, wr, wc, fr, fq); S.done(cur); }
;         if (!has_next) break;
; #pragma unroll
;         for (int a = 0; a < 2; ++a)
; #pragma unroll
;             for (int b = 0; b < 2; ++b)
; #pragma unroll
;                 for (int m = 0; m < 4; ++m)
; #pragma unroll
;                     for (int n = 0; n < 2; ++n) acc[a][b][m][n] = (f32x4){0.f, 0.f, 0.f, 0.f};
;         cur = nxt; cA = nA; cB = nB; ++ui;
;         if constexpr (ALIGN_EPI) { if (wr == 1) PG8_BAR; }
;     __device__ __forceinline__ void operator()(const f32x4 (&acc)[2][2][4][2], const pg8::Unit& u, int wr, int wc, int fr, int fq) const {
;     ...
;         for (int ai = 0; ai < 2; ++ai)
; #pragma unroll
;             for (int m = 0; m < 4; ++m) {
;                 const int row = u.pm * 256 + ai * 128 + wr * 64 + m * 16 + fr;
;                 const float tot = (sq[ai][m].x + sq[ai][m].y) + (sq[ai][m].z + sq[ai][m].w);
;                 const float rn = rsqrtf(tot * (1.f / 1024.f) + EPS);
; #pragma unroll
;                 for (int bj = 0; bj < 2; ++bj) {
;                     float y[8];
; #pragma unroll
;                     for (int n = 0; n < 2; ++n)
; #pragma unroll
;                         for (int e = 0; e < 4; ++e) { const float h = fmaxf(acc[ai][bj][m][n][e] * rn, 0.f); y[n * 4 + e] = h * h; }
;                     store8(H + (size_t)row * FF + u.pn * 256 + 128 * bj + 32 * wc + 8 * fq, y);
;                 }
	v_mul_f32_e32 v40, v43, v50
	v_lshlrev_b64 v[48:49], 13, v[168:169]
	v_mul_f32_e32 v52, v44, v44
	v_mul_f32_e32 v44, v46, v50
	v_mul_f32_e32 v43, v40, v40
	v_lshl_add_u64 v[40:41], s[10:11], 0, v[48:49]
	v_mul_f32_e32 v46, v44, v44
	v_mul_f32_e32 v44, v47, v50
	v_lshl_add_u64 v[40:41], v[40:41], 0, s[30:31]
	v_lshl_add_u64 v[40:41], v[40:41], 0, s[4:5]
	v_mul_f32_e32 v32, v32, v50
	v_mul_f32_e32 v47, v44, v44
	v_lshl_add_u64 v[44:45], v[40:41], 0, v[152:153]
	v_cvt_pk_bf16_f32 v40, v51, v52
	v_cvt_pk_bf16_f32 v41, v46, v47
	v_cvt_pk_bf16_f32 v42, v53, v54
	v_cvt_pk_bf16_f32 v43, v55, v43
	global_store_dwordx4 v[44:45], v[40:43], off nt
	v_mul_f32_e32 v36, v36, v50
	v_mul_f32_e32 v37, v37, v50
	v_mul_f32_e32 v40, v32, v32
	v_mul_f32_e32 v32, v33, v50
	v_mul_f32_e32 v41, v32, v32
	v_mul_f32_e32 v32, v34, v50
	v_mul_f32_e32 v38, v38, v50
	v_mul_f32_e32 v39, v39, v50
	v_mul_f32_e32 v42, v32, v32
	v_mul_f32_e32 v32, v35, v50
	v_mul_f32_e32 v36, v36, v36
	v_mul_f32_e32 v37, v37, v37
	v_mul_f32_e32 v38, v38, v38
	v_mul_f32_e32 v39, v39, v39
	v_mul_f32_e32 v35, v32, v32
	v_cvt_pk_bf16_f32 v32, v36, v37
	v_cvt_pk_bf16_f32 v33, v38, v39
	v_cvt_pk_bf16_f32 v34, v40, v41
	v_cvt_pk_bf16_f32 v35, v42, v35
	global_store_dwordx4 v[44:45], v[32:35], off offset:256 nt
	v_mov_b32_e32 v36, v129
	v_mov_b32_e32 v37, v130
	v_mov_b32_e32 v32, v133
	v_mov_b32_e32 v33, v134
	v_mov_b32_e32 v133, v135
	v_mov_b32_e32 v129, v131
	v_pk_add_f32 v[32:33], v[32:33], v[132:133]
	v_pk_add_f32 v[36:37], v[36:37], v[128:129]
	v_mov_b32_e32 v39, v32
	v_mov_b32_e32 v38, v36
	v_mov_b32_e32 v32, v37
	v_pk_add_f32 v[32:33], v[38:39], v[32:33]
	v_lshlrev_b64 v[34:35], 13, v[164:165]
	v_pk_fma_f32 v[32:33], v[32:33], s[18:19], v[166:167] op_sel_hi:[1,0,0]
	v_lshl_add_u64 v[34:35], s[10:11], 0, v[34:35]
	v_mul_f32_e32 v36, 0x4b800000, v33
	v_cmp_gt_f32_e32 vcc, s50, v33
	v_lshl_add_u64 v[34:35], v[34:35], 0, s[30:31]
	v_lshl_add_u64 v[34:35], v[34:35], 0, s[4:5]
	v_cndmask_b32_e32 v33, v33, v36, vcc
	v_rsq_f32_e32 v33, v33
	v_lshl_add_u64 v[34:35], v[34:35], 0, v[152:153]
	v_mul_f32_e32 v36, 0x45800000, v33
	v_cndmask_b32_e32 v33, v33, v36, vcc
	v_mul_f32_e32 v24, v24, v33
	v_mul_f32_e32 v36, v24, v24
	v_mul_f32_e32 v24, v25, v33
	v_mul_f32_e32 v37, v24, v24
	v_mul_f32_e32 v24, v26, v33
	v_mul_f32_e32 v28, v28, v33
	v_mul_f32_e32 v29, v29, v33
	v_mul_f32_e32 v38, v24, v24
	v_mul_f32_e32 v24, v27, v33
	v_mul_f32_e32 v30, v30, v33
	v_mul_f32_e32 v31, v31, v33
	v_mul_f32_e32 v16, v16, v33
	v_mul_f32_e32 v28, v28, v28
	v_mul_f32_e32 v29, v29, v29
	v_mul_f32_e32 v27, v24, v24
	v_cvt_pk_bf16_f32 v24, v28, v29
	v_mul_f32_e32 v30, v30, v30
	v_mul_f32_e32 v31, v31, v31
	v_cvt_pk_bf16_f32 v25, v30, v31
	v_cvt_pk_bf16_f32 v26, v36, v37
	v_cvt_pk_bf16_f32 v27, v38, v27
	global_store_dwordx4 v[34:35], v[24:27], off nt
	v_mul_f32_e32 v20, v20, v33
	s_nop 0
	v_mul_f32_e32 v24, v16, v16
	v_mul_f32_e32 v16, v17, v33
	v_mul_f32_e32 v25, v16, v16
	v_mul_f32_e32 v16, v18, v33
	v_mul_f32_e32 v21, v21, v33
	v_mul_f32_e32 v26, v16, v16
	v_mul_f32_e32 v16, v19, v33
	v_mul_f32_e32 v18, 0x4b800000, v32
	v_cmp_gt_f32_e32 vcc, s50, v32
	v_mul_f32_e32 v20, v20, v20
	s_nop 0
	v_cndmask_b32_e32 v18, v32, v18, vcc
	v_mul_f32_e32 v21, v21, v21
	v_mul_f32_e32 v19, v16, v16
	v_cvt_pk_bf16_f32 v16, v20, v21
	v_rsq_f32_e32 v20, v18
	v_mul_f32_e32 v22, v22, v33
	v_mul_f32_e32 v23, v23, v33
	v_mul_f32_e32 v22, v22, v22
	v_mul_f32_e32 v23, v23, v23
	v_cvt_pk_bf16_f32 v17, v22, v23
	v_cvt_pk_bf16_f32 v18, v24, v25
	v_cvt_pk_bf16_f32 v19, v26, v19
	global_store_dwordx4 v[34:35], v[16:19], off offset:256 nt
	s_nop 1
	v_mul_f32_e32 v16, 0x45800000, v20
	v_cndmask_b32_e32 v18, v20, v16, vcc
	v_mul_f32_e32 v8, v8, v18
	v_mul_f32_e32 v21, v8, v8
	v_mul_f32_e32 v8, v9, v18
	v_mul_f32_e32 v12, v12, v18
	v_mul_f32_e32 v22, v8, v8
	v_mul_f32_e32 v8, v10, v18
	v_mul_f32_e32 v19, v12, v12
	v_mul_f32_e32 v12, v13, v18
	v_mul_f32_e32 v23, v8, v8
	v_mul_f32_e32 v8, v11, v18
	v_lshlrev_b64 v[16:17], 13, v[162:163]
	v_mul_f32_e32 v20, v12, v12
	v_mul_f32_e32 v12, v14, v18
	v_mul_f32_e32 v11, v8, v8
	v_lshl_add_u64 v[8:9], s[10:11], 0, v[16:17]
	v_mul_f32_e32 v14, v12, v12
	v_mul_f32_e32 v12, v15, v18
	v_lshl_add_u64 v[8:9], v[8:9], 0, s[30:31]
	v_lshl_add_u64 v[8:9], v[8:9], 0, s[4:5]
	v_mul_f32_e32 v0, v0, v18
	v_mul_f32_e32 v15, v12, v12
	v_lshl_add_u64 v[12:13], v[8:9], 0, v[152:153]
	v_cvt_pk_bf16_f32 v8, v19, v20
	v_cvt_pk_bf16_f32 v9, v14, v15
	v_cvt_pk_bf16_f32 v10, v21, v22
	v_cvt_pk_bf16_f32 v11, v23, v11
	global_store_dwordx4 v[12:13], v[8:11], off nt
	v_mul_f32_e32 v4, v4, v18
	v_mul_f32_e32 v5, v5, v18
	v_mul_f32_e32 v8, v0, v0
	v_mul_f32_e32 v0, v1, v18
	v_mul_f32_e32 v9, v0, v0
	v_mul_f32_e32 v0, v2, v18
	v_mul_f32_e32 v10, v0, v0
	v_mul_f32_e32 v0, v3, v18
	v_mul_f32_e32 v6, v6, v18
	v_mul_f32_e32 v7, v7, v18
	v_mul_f32_e32 v3, v0, v0
	s_andn2_b64 vcc, exec, s[2:3]
	s_mov_b64 s[2:3], -1
	v_mul_f32_e32 v4, v4, v4
	v_mul_f32_e32 v5, v5, v5
	v_mul_f32_e32 v6, v6, v6
	v_mul_f32_e32 v7, v7, v7
	v_cvt_pk_bf16_f32 v0, v4, v5
	v_cvt_pk_bf16_f32 v1, v6, v7
	v_cvt_pk_bf16_f32 v2, v8, v9
	v_cvt_pk_bf16_f32 v3, v10, v3
	global_store_dwordx4 v[12:13], v[0:3], off offset:256 nt
	s_cbranch_vccnz .LBB0_999
	s_andn2_b64 vcc, exec, s[6:7]
	s_cbranch_vccnz .LBB0_998
	s_barrier
	s_branch .LBB0_998
